# c4 plus: sample-row 64x64 GEMM tiles (gate and w_out/w_o instances) issue all fragment loads of 8 k-steps before the MFMAs instead of one round trip per k-step
# speedup vs baseline: 1.0039x; 1.0039x over previous
.LBB0_179:
	v_lshl_add_u64 v[44:45], v[38:39], 0, s[16:17]
	v_add_co_u32_e32 v46, vcc, s70, v44
	v_lshl_add_u64 v[50:51], v[36:37], 0, s[16:17]
	s_nop 0
	v_addc_co_u32_e32 v47, vcc, 0, v45, vcc
	s_mov_b32 s26, 0x3500000
	v_add_co_u32_e32 v40, vcc, s26, v50
	s_mov_b32 s26, 0x3508000
	s_nop 0
	v_addc_co_u32_e32 v41, vcc, 0, v51, vcc
	v_add_co_u32_e32 v42, vcc, s26, v50
	s_mov_b32 s26, 0x3510000
	s_nop 0
	v_addc_co_u32_e32 v43, vcc, 0, v51, vcc
	v_add_co_u32_e32 v48, vcc, s26, v50
	s_mov_b32 s26, 0x3518000
	s_nop 0
	v_addc_co_u32_e32 v49, vcc, 0, v51, vcc
	v_add_co_u32_e32 v50, vcc, s26, v50
	s_nop 1
	v_addc_co_u32_e32 v51, vcc, 0, v51, vcc
	global_load_dwordx4 v[58:61], v[44:45], off
	global_load_dwordx4 v[62:65], v[46:47], off
	global_load_dwordx4 v[66:69], v[40:41], off
	global_load_dwordx4 v[70:73], v[42:43], off
	global_load_dwordx4 v[74:77], v[48:49], off
	global_load_dwordx4 v[78:81], v[50:51], off
	global_load_dwordx4 v[82:85], v[44:45], off offset:64
	global_load_dwordx4 v[86:89], v[46:47], off offset:64
	global_load_dwordx4 v[90:93], v[40:41], off offset:64
	global_load_dwordx4 v[94:97], v[42:43], off offset:64
	global_load_dwordx4 v[98:101], v[48:49], off offset:64
	global_load_dwordx4 v[102:105], v[50:51], off offset:64
	global_load_dwordx4 v[106:109], v[44:45], off offset:128
	global_load_dwordx4 v[110:113], v[46:47], off offset:128
	global_load_dwordx4 v[114:117], v[40:41], off offset:128
	global_load_dwordx4 v[118:121], v[42:43], off offset:128
	global_load_dwordx4 v[122:125], v[48:49], off offset:128
	global_load_dwordx4 v[126:129], v[50:51], off offset:128
	global_load_dwordx4 v[130:133], v[44:45], off offset:192
	global_load_dwordx4 v[134:137], v[46:47], off offset:192
	global_load_dwordx4 v[138:141], v[40:41], off offset:192
	global_load_dwordx4 v[146:149], v[42:43], off offset:192
	global_load_dwordx4 v[150:153], v[48:49], off offset:192
	global_load_dwordx4 v[154:157], v[50:51], off offset:192
	global_load_dwordx4 v[160:163], v[44:45], off offset:256
	global_load_dwordx4 v[164:167], v[46:47], off offset:256
	global_load_dwordx4 v[168:171], v[40:41], off offset:256
	global_load_dwordx4 v[172:175], v[42:43], off offset:256
	global_load_dwordx4 v[176:179], v[48:49], off offset:256
	global_load_dwordx4 v[180:183], v[50:51], off offset:256
	global_load_dwordx4 v[184:187], v[44:45], off offset:320
	global_load_dwordx4 v[188:191], v[46:47], off offset:320
	global_load_dwordx4 v[192:195], v[40:41], off offset:320
	global_load_dwordx4 v[196:199], v[42:43], off offset:320
	global_load_dwordx4 v[200:203], v[48:49], off offset:320
	global_load_dwordx4 v[204:207], v[50:51], off offset:320
	global_load_dwordx4 v[208:211], v[44:45], off offset:384
	global_load_dwordx4 v[212:215], v[46:47], off offset:384
	global_load_dwordx4 v[216:219], v[40:41], off offset:384
	global_load_dwordx4 v[220:223], v[42:43], off offset:384
	global_load_dwordx4 v[224:227], v[48:49], off offset:384
	global_load_dwordx4 v[228:231], v[50:51], off offset:384
	global_load_dwordx4 v[232:235], v[44:45], off offset:448
	global_load_dwordx4 v[236:239], v[46:47], off offset:448
	global_load_dwordx4 v[244:247], v[40:41], off offset:448
	global_load_dwordx4 v[248:251], v[42:43], off offset:448
	global_load_dwordx4 v[44:47], v[48:49], off offset:448
	global_load_dwordx4 v[40:43], v[50:51], off offset:448
	s_waitcnt vmcnt(42)
	v_mfma_f32_16x16x32_bf16 v[28:31], v[66:69], v[58:61], v[28:31]
	v_mfma_f32_16x16x32_bf16 v[24:27], v[70:73], v[58:61], v[24:27]
	v_mfma_f32_16x16x32_bf16 v[20:23], v[74:77], v[58:61], v[20:23]
	v_mfma_f32_16x16x32_bf16 v[16:19], v[78:81], v[58:61], v[16:19]
	v_mfma_f32_16x16x32_bf16 v[12:15], v[66:69], v[62:65], v[12:15]
	v_mfma_f32_16x16x32_bf16 v[8:11], v[70:73], v[62:65], v[8:11]
	v_mfma_f32_16x16x32_bf16 v[4:7], v[74:77], v[62:65], v[4:7]
	v_mfma_f32_16x16x32_bf16 v[0:3], v[78:81], v[62:65], v[0:3]
	s_waitcnt vmcnt(36)
	v_mfma_f32_16x16x32_bf16 v[28:31], v[90:93], v[82:85], v[28:31]
	v_mfma_f32_16x16x32_bf16 v[24:27], v[94:97], v[82:85], v[24:27]
	v_mfma_f32_16x16x32_bf16 v[20:23], v[98:101], v[82:85], v[20:23]
	v_mfma_f32_16x16x32_bf16 v[16:19], v[102:105], v[82:85], v[16:19]
	v_mfma_f32_16x16x32_bf16 v[12:15], v[90:93], v[86:89], v[12:15]
	v_mfma_f32_16x16x32_bf16 v[8:11], v[94:97], v[86:89], v[8:11]
	v_mfma_f32_16x16x32_bf16 v[4:7], v[98:101], v[86:89], v[4:7]
	v_mfma_f32_16x16x32_bf16 v[0:3], v[102:105], v[86:89], v[0:3]
	s_waitcnt vmcnt(30)
	v_mfma_f32_16x16x32_bf16 v[28:31], v[114:117], v[106:109], v[28:31]
	v_mfma_f32_16x16x32_bf16 v[24:27], v[118:121], v[106:109], v[24:27]
	v_mfma_f32_16x16x32_bf16 v[20:23], v[122:125], v[106:109], v[20:23]
	v_mfma_f32_16x16x32_bf16 v[16:19], v[126:129], v[106:109], v[16:19]
	v_mfma_f32_16x16x32_bf16 v[12:15], v[114:117], v[110:113], v[12:15]
	v_mfma_f32_16x16x32_bf16 v[8:11], v[118:121], v[110:113], v[8:11]
	v_mfma_f32_16x16x32_bf16 v[4:7], v[122:125], v[110:113], v[4:7]
	v_mfma_f32_16x16x32_bf16 v[0:3], v[126:129], v[110:113], v[0:3]
	s_waitcnt vmcnt(24)
	v_mfma_f32_16x16x32_bf16 v[28:31], v[138:141], v[130:133], v[28:31]
	v_mfma_f32_16x16x32_bf16 v[24:27], v[146:149], v[130:133], v[24:27]
	v_mfma_f32_16x16x32_bf16 v[20:23], v[150:153], v[130:133], v[20:23]
	v_mfma_f32_16x16x32_bf16 v[16:19], v[154:157], v[130:133], v[16:19]
	v_mfma_f32_16x16x32_bf16 v[12:15], v[138:141], v[134:137], v[12:15]
	v_mfma_f32_16x16x32_bf16 v[8:11], v[146:149], v[134:137], v[8:11]
	v_mfma_f32_16x16x32_bf16 v[4:7], v[150:153], v[134:137], v[4:7]
	v_mfma_f32_16x16x32_bf16 v[0:3], v[154:157], v[134:137], v[0:3]
	s_waitcnt vmcnt(18)
	v_mfma_f32_16x16x32_bf16 v[28:31], v[168:171], v[160:163], v[28:31]
	v_mfma_f32_16x16x32_bf16 v[24:27], v[172:175], v[160:163], v[24:27]
	v_mfma_f32_16x16x32_bf16 v[20:23], v[176:179], v[160:163], v[20:23]
	v_mfma_f32_16x16x32_bf16 v[16:19], v[180:183], v[160:163], v[16:19]
	v_mfma_f32_16x16x32_bf16 v[12:15], v[168:171], v[164:167], v[12:15]
	v_mfma_f32_16x16x32_bf16 v[8:11], v[172:175], v[164:167], v[8:11]
	v_mfma_f32_16x16x32_bf16 v[4:7], v[176:179], v[164:167], v[4:7]
	v_mfma_f32_16x16x32_bf16 v[0:3], v[180:183], v[164:167], v[0:3]
	s_waitcnt vmcnt(12)
	v_mfma_f32_16x16x32_bf16 v[28:31], v[192:195], v[184:187], v[28:31]
	v_mfma_f32_16x16x32_bf16 v[24:27], v[196:199], v[184:187], v[24:27]
	v_mfma_f32_16x16x32_bf16 v[20:23], v[200:203], v[184:187], v[20:23]
	v_mfma_f32_16x16x32_bf16 v[16:19], v[204:207], v[184:187], v[16:19]
	v_mfma_f32_16x16x32_bf16 v[12:15], v[192:195], v[188:191], v[12:15]
	v_mfma_f32_16x16x32_bf16 v[8:11], v[196:199], v[188:191], v[8:11]
	v_mfma_f32_16x16x32_bf16 v[4:7], v[200:203], v[188:191], v[4:7]
	v_mfma_f32_16x16x32_bf16 v[0:3], v[204:207], v[188:191], v[0:3]
	s_waitcnt vmcnt(6)
	v_mfma_f32_16x16x32_bf16 v[28:31], v[216:219], v[208:211], v[28:31]
	v_mfma_f32_16x16x32_bf16 v[24:27], v[220:223], v[208:211], v[24:27]
	v_mfma_f32_16x16x32_bf16 v[20:23], v[224:227], v[208:211], v[20:23]
	v_mfma_f32_16x16x32_bf16 v[16:19], v[228:231], v[208:211], v[16:19]
	v_mfma_f32_16x16x32_bf16 v[12:15], v[216:219], v[212:215], v[12:15]
	v_mfma_f32_16x16x32_bf16 v[8:11], v[220:223], v[212:215], v[8:11]
	v_mfma_f32_16x16x32_bf16 v[4:7], v[224:227], v[212:215], v[4:7]
	v_mfma_f32_16x16x32_bf16 v[0:3], v[228:231], v[212:215], v[0:3]
	s_waitcnt vmcnt(0)
	v_mfma_f32_16x16x32_bf16 v[28:31], v[244:247], v[232:235], v[28:31]
	v_mfma_f32_16x16x32_bf16 v[24:27], v[248:251], v[232:235], v[24:27]
	v_mfma_f32_16x16x32_bf16 v[20:23], v[44:47], v[232:235], v[20:23]
	v_mfma_f32_16x16x32_bf16 v[16:19], v[40:43], v[232:235], v[16:19]
	v_mfma_f32_16x16x32_bf16 v[12:15], v[244:247], v[236:239], v[12:15]
	v_mfma_f32_16x16x32_bf16 v[8:11], v[248:251], v[236:239], v[8:11]
	v_mfma_f32_16x16x32_bf16 v[4:7], v[44:47], v[236:239], v[4:7]
	v_mfma_f32_16x16x32_bf16 v[0:3], v[40:43], v[236:239], v[0:3]
	ds_write_b128 v56, v[28:31]
	ds_write_b128 v56, v[24:27] offset:64
	ds_write_b128 v56, v[20:23] offset:128
	ds_write_b128 v56, v[16:19] offset:192
	ds_write_b128 v56, v[12:15] offset:4352
	ds_write_b128 v56, v[8:11] offset:4416
	ds_write_b128 v56, v[4:7] offset:4480
	ds_write_b128 v56, v[0:3] offset:4544
	s_waitcnt lgkmcnt(0)
	s_barrier
	ds_read_b128 v[4:7], v57
	ds_read_b128 v[0:3], v57 offset:16
	s_addk_i32 s5, 0x4000
	s_lshl_b32 s4, s4, 4
	s_sub_i32 s4, s15, s4
	s_waitcnt lgkmcnt(1)
	v_pk_add_f32 v[8:9], v[6:7], 0 op_sel_hi:[1,0]
	v_pk_add_f32 v[10:11], v[4:5], 0 op_sel_hi:[1,0]
	ds_read_b128 v[4:7], v57 offset:17408
	s_and_b64 vcc, exec, s[24:25]
	s_waitcnt lgkmcnt(0)
	v_pk_add_f32 v[12:13], v[8:9], v[6:7]
	v_pk_add_f32 v[14:15], v[10:11], v[4:5]
	ds_read_b128 v[4:7], v57 offset:17424
	ds_read_b128 v[8:11], v57 offset:34816
	s_waitcnt lgkmcnt(0)
	v_pk_add_f32 v[16:17], v[12:13], v[10:11]
	v_pk_add_f32 v[18:19], v[14:15], v[8:9]
	ds_read_b128 v[8:11], v57 offset:34832
	ds_read_b128 v[12:15], v57 offset:52224
	s_waitcnt lgkmcnt(0)
	v_pk_add_f32 v[22:23], v[16:17], v[14:15]
	v_add_u32_e32 v16, s5, v53
	v_pk_add_f32 v[30:31], v[18:19], v[12:13]
	v_lshl_or_b32 v18, s4, 6, v54
	v_ashrrev_i32_e32 v17, 31, v16
	v_lshlrev_b64 v[16:17], 10, v[16:17]
	v_ashrrev_i32_e32 v19, 31, v18
	v_lshl_add_u64 v[20:21], v[16:17], 0, v[18:19]
	v_readlane_b32 s4, v254, 51
	v_lshlrev_b64 v[16:17], 1, v[20:21]
	v_readlane_b32 s5, v254, 52
	v_lshl_add_u64 v[24:25], v[18:19], 2, s[10:11]
	v_lshl_add_u64 v[28:29], s[8:9], 0, v[16:17]
	v_lshl_add_u64 v[26:27], s[4:5], 0, v[16:17]
	global_load_dwordx4 v[16:19], v[24:25], off
	global_load_dwordx2 v[36:37], v[26:27], off
	global_load_dwordx2 v[38:39], v[28:29], off
	ds_read_b128 v[12:15], v57 offset:52240
	s_waitcnt vmcnt(2)
	v_pk_add_f32 v[16:17], v[30:31], v[16:17]
	v_pk_add_f32 v[18:19], v[22:23], v[18:19]
	v_mul_f32_e32 v16, 0xbfb8aa3b, v16
	v_mul_f32_e32 v17, 0xbfb8aa3b, v17
	v_exp_f32_e32 v16, v16
	v_exp_f32_e32 v17, v17
	v_mul_f32_e32 v18, 0xbfb8aa3b, v18
	v_mul_f32_e32 v19, 0xbfb8aa3b, v19
	v_exp_f32_e32 v18, v18
	v_exp_f32_e32 v19, v19
	v_add_f32_e32 v16, 1.0, v16
	v_add_f32_e32 v17, 1.0, v17
	v_rcp_f32_e32 v16, v16
	v_rcp_f32_e32 v17, v17
	v_add_f32_e32 v18, 1.0, v18
	v_add_f32_e32 v19, 1.0, v19
	v_rcp_f32_e32 v18, v18
	v_rcp_f32_e32 v19, v19
	s_waitcnt vmcnt(1)
	v_lshlrev_b32_e32 v22, 16, v36
	v_and_b32_e32 v23, 0xffff0000, v36
	s_waitcnt vmcnt(0)
	v_lshlrev_b32_e32 v30, 16, v38
	v_and_b32_e32 v31, 0xffff0000, v38
	v_pk_fma_f32 v[16:17], v[16:17], v[30:31], v[22:23]
	v_lshlrev_b32_e32 v22, 16, v37
	v_and_b32_e32 v23, 0xffff0000, v37
	v_lshlrev_b32_e32 v30, 16, v39
	v_and_b32_e32 v31, 0xffff0000, v39
	v_pk_fma_f32 v[18:19], v[18:19], v[30:31], v[22:23]
	v_lshl_add_u64 v[22:23], v[20:21], 2, s[88:89]
	s_cbranch_vccz .LBB0_185
	global_store_dwordx4 v[22:23], v[16:19], off
	s_cbranch_execnz .LBB0_183

.LBB0_458:
	v_lshl_add_u64 v[54:55], v[32:33], 0, s[30:31]
	v_lshl_add_u64 v[56:57], v[34:35], 0, s[30:31]
	v_lshl_add_u64 v[58:59], v[36:37], 0, s[30:31]
	v_lshl_add_u64 v[60:61], v[46:47], 0, s[30:31]
	v_lshl_add_u64 v[62:63], v[38:39], 0, s[30:31]
	v_lshl_add_u64 v[64:65], v[44:45], 0, s[30:31]
	global_load_dwordx4 v[66:69], v[54:55], off
	global_load_dwordx4 v[70:73], v[56:57], off
	global_load_dwordx4 v[74:77], v[58:59], off
	global_load_dwordx4 v[78:81], v[60:61], off
	global_load_dwordx4 v[82:85], v[62:63], off
	global_load_dwordx4 v[86:89], v[64:65], off
	global_load_dwordx4 v[90:93], v[54:55], off offset:64
	global_load_dwordx4 v[94:97], v[56:57], off offset:64
	global_load_dwordx4 v[98:101], v[58:59], off offset:64
	global_load_dwordx4 v[102:105], v[60:61], off offset:64
	global_load_dwordx4 v[106:109], v[62:63], off offset:64
	global_load_dwordx4 v[110:113], v[64:65], off offset:64
	global_load_dwordx4 v[114:117], v[54:55], off offset:128
	global_load_dwordx4 v[118:121], v[56:57], off offset:128
	global_load_dwordx4 v[122:125], v[58:59], off offset:128
	global_load_dwordx4 v[126:129], v[60:61], off offset:128
	global_load_dwordx4 v[130:133], v[62:63], off offset:128
	global_load_dwordx4 v[134:137], v[64:65], off offset:128
	global_load_dwordx4 v[138:141], v[54:55], off offset:192
	global_load_dwordx4 v[146:149], v[56:57], off offset:192
	global_load_dwordx4 v[150:153], v[58:59], off offset:192
	global_load_dwordx4 v[154:157], v[60:61], off offset:192
	global_load_dwordx4 v[160:163], v[62:63], off offset:192
	global_load_dwordx4 v[164:167], v[64:65], off offset:192
	global_load_dwordx4 v[168:171], v[54:55], off offset:256
	global_load_dwordx4 v[172:175], v[56:57], off offset:256
	global_load_dwordx4 v[176:179], v[58:59], off offset:256
	global_load_dwordx4 v[180:183], v[60:61], off offset:256
	global_load_dwordx4 v[184:187], v[62:63], off offset:256
	global_load_dwordx4 v[188:191], v[64:65], off offset:256
	global_load_dwordx4 v[192:195], v[54:55], off offset:320
	global_load_dwordx4 v[196:199], v[56:57], off offset:320
	global_load_dwordx4 v[200:203], v[58:59], off offset:320
	global_load_dwordx4 v[204:207], v[60:61], off offset:320
	global_load_dwordx4 v[208:211], v[62:63], off offset:320
	global_load_dwordx4 v[212:215], v[64:65], off offset:320
	global_load_dwordx4 v[216:219], v[54:55], off offset:384
	global_load_dwordx4 v[220:223], v[56:57], off offset:384
	global_load_dwordx4 v[224:227], v[58:59], off offset:384
	global_load_dwordx4 v[228:231], v[60:61], off offset:384
	global_load_dwordx4 v[232:235], v[62:63], off offset:384
	global_load_dwordx4 v[236:239], v[64:65], off offset:384
	v_add_co_u32_e32 v32, vcc, 0x200, v32
	s_nop 1
	v_addc_co_u32_e32 v33, vcc, 0, v33, vcc
	v_add_co_u32_e32 v34, vcc, 0x200, v34
	s_nop 1
	v_addc_co_u32_e32 v35, vcc, 0, v35, vcc
	v_add_co_u32_e32 v36, vcc, 0x200, v36
	s_nop 1
	v_addc_co_u32_e32 v37, vcc, 0, v37, vcc
	v_add_co_u32_e32 v46, vcc, 0x200, v46
	s_nop 1
	v_addc_co_u32_e32 v47, vcc, 0, v47, vcc
	v_add_co_u32_e32 v38, vcc, 0x200, v38
	s_nop 1
	v_addc_co_u32_e32 v39, vcc, 0, v39, vcc
	v_add_co_u32_e32 v44, vcc, 0x200, v44
	s_nop 1
	v_addc_co_u32_e32 v45, vcc, 0, v45, vcc
	s_add_i32 s25, s25, -8
	s_cmp_eq_u32 s25, 0
	s_waitcnt vmcnt(36)
	v_mfma_f32_16x16x32_bf16 v[28:31], v[74:77], v[66:69], v[28:31]
	v_mfma_f32_16x16x32_bf16 v[24:27], v[78:81], v[66:69], v[24:27]
	v_mfma_f32_16x16x32_bf16 v[20:23], v[82:85], v[66:69], v[20:23]
	v_mfma_f32_16x16x32_bf16 v[16:19], v[86:89], v[66:69], v[16:19]
	v_mfma_f32_16x16x32_bf16 v[12:15], v[74:77], v[70:73], v[12:15]
	v_mfma_f32_16x16x32_bf16 v[8:11], v[78:81], v[70:73], v[8:11]
	v_mfma_f32_16x16x32_bf16 v[4:7], v[82:85], v[70:73], v[4:7]
	v_mfma_f32_16x16x32_bf16 v[0:3], v[86:89], v[70:73], v[0:3]
	global_load_dwordx4 v[66:69], v[54:55], off offset:448
	global_load_dwordx4 v[70:73], v[56:57], off offset:448
	global_load_dwordx4 v[74:77], v[58:59], off offset:448
	global_load_dwordx4 v[78:81], v[60:61], off offset:448
	global_load_dwordx4 v[82:85], v[62:63], off offset:448
	global_load_dwordx4 v[86:89], v[64:65], off offset:448
	s_waitcnt vmcnt(36)
	v_mfma_f32_16x16x32_bf16 v[28:31], v[98:101], v[90:93], v[28:31]
	v_mfma_f32_16x16x32_bf16 v[24:27], v[102:105], v[90:93], v[24:27]
	v_mfma_f32_16x16x32_bf16 v[20:23], v[106:109], v[90:93], v[20:23]
	v_mfma_f32_16x16x32_bf16 v[16:19], v[110:113], v[90:93], v[16:19]
	v_mfma_f32_16x16x32_bf16 v[12:15], v[98:101], v[94:97], v[12:15]
	v_mfma_f32_16x16x32_bf16 v[8:11], v[102:105], v[94:97], v[8:11]
	v_mfma_f32_16x16x32_bf16 v[4:7], v[106:109], v[94:97], v[4:7]
	v_mfma_f32_16x16x32_bf16 v[0:3], v[110:113], v[94:97], v[0:3]
	s_waitcnt vmcnt(30)
	v_mfma_f32_16x16x32_bf16 v[28:31], v[122:125], v[114:117], v[28:31]
	v_mfma_f32_16x16x32_bf16 v[24:27], v[126:129], v[114:117], v[24:27]
	v_mfma_f32_16x16x32_bf16 v[20:23], v[130:133], v[114:117], v[20:23]
	v_mfma_f32_16x16x32_bf16 v[16:19], v[134:137], v[114:117], v[16:19]
	v_mfma_f32_16x16x32_bf16 v[12:15], v[122:125], v[118:121], v[12:15]
	v_mfma_f32_16x16x32_bf16 v[8:11], v[126:129], v[118:121], v[8:11]
	v_mfma_f32_16x16x32_bf16 v[4:7], v[130:133], v[118:121], v[4:7]
	v_mfma_f32_16x16x32_bf16 v[0:3], v[134:137], v[118:121], v[0:3]
	s_waitcnt vmcnt(24)
	v_mfma_f32_16x16x32_bf16 v[28:31], v[150:153], v[138:141], v[28:31]
	v_mfma_f32_16x16x32_bf16 v[24:27], v[154:157], v[138:141], v[24:27]
	v_mfma_f32_16x16x32_bf16 v[20:23], v[160:163], v[138:141], v[20:23]
	v_mfma_f32_16x16x32_bf16 v[16:19], v[164:167], v[138:141], v[16:19]
	v_mfma_f32_16x16x32_bf16 v[12:15], v[150:153], v[146:149], v[12:15]
	v_mfma_f32_16x16x32_bf16 v[8:11], v[154:157], v[146:149], v[8:11]
	v_mfma_f32_16x16x32_bf16 v[4:7], v[160:163], v[146:149], v[4:7]
	v_mfma_f32_16x16x32_bf16 v[0:3], v[164:167], v[146:149], v[0:3]
	s_waitcnt vmcnt(18)
	v_mfma_f32_16x16x32_bf16 v[28:31], v[176:179], v[168:171], v[28:31]
	v_mfma_f32_16x16x32_bf16 v[24:27], v[180:183], v[168:171], v[24:27]
	v_mfma_f32_16x16x32_bf16 v[20:23], v[184:187], v[168:171], v[20:23]
	v_mfma_f32_16x16x32_bf16 v[16:19], v[188:191], v[168:171], v[16:19]
	v_mfma_f32_16x16x32_bf16 v[12:15], v[176:179], v[172:175], v[12:15]
	v_mfma_f32_16x16x32_bf16 v[8:11], v[180:183], v[172:175], v[8:11]
	v_mfma_f32_16x16x32_bf16 v[4:7], v[184:187], v[172:175], v[4:7]
	v_mfma_f32_16x16x32_bf16 v[0:3], v[188:191], v[172:175], v[0:3]
	s_waitcnt vmcnt(12)
	v_mfma_f32_16x16x32_bf16 v[28:31], v[200:203], v[192:195], v[28:31]
	v_mfma_f32_16x16x32_bf16 v[24:27], v[204:207], v[192:195], v[24:27]
	v_mfma_f32_16x16x32_bf16 v[20:23], v[208:211], v[192:195], v[20:23]
	v_mfma_f32_16x16x32_bf16 v[16:19], v[212:215], v[192:195], v[16:19]
	v_mfma_f32_16x16x32_bf16 v[12:15], v[200:203], v[196:199], v[12:15]
	v_mfma_f32_16x16x32_bf16 v[8:11], v[204:207], v[196:199], v[8:11]
	v_mfma_f32_16x16x32_bf16 v[4:7], v[208:211], v[196:199], v[4:7]
	v_mfma_f32_16x16x32_bf16 v[0:3], v[212:215], v[196:199], v[0:3]
	s_waitcnt vmcnt(6)
	v_mfma_f32_16x16x32_bf16 v[28:31], v[224:227], v[216:219], v[28:31]
	v_mfma_f32_16x16x32_bf16 v[24:27], v[228:231], v[216:219], v[24:27]
	v_mfma_f32_16x16x32_bf16 v[20:23], v[232:235], v[216:219], v[20:23]
	v_mfma_f32_16x16x32_bf16 v[16:19], v[236:239], v[216:219], v[16:19]
	v_mfma_f32_16x16x32_bf16 v[12:15], v[224:227], v[220:223], v[12:15]
	v_mfma_f32_16x16x32_bf16 v[8:11], v[228:231], v[220:223], v[8:11]
	v_mfma_f32_16x16x32_bf16 v[4:7], v[232:235], v[220:223], v[4:7]
	v_mfma_f32_16x16x32_bf16 v[0:3], v[236:239], v[220:223], v[0:3]
	s_waitcnt vmcnt(0)
	v_mfma_f32_16x16x32_bf16 v[28:31], v[74:77], v[66:69], v[28:31]
	v_mfma_f32_16x16x32_bf16 v[24:27], v[78:81], v[66:69], v[24:27]
	v_mfma_f32_16x16x32_bf16 v[20:23], v[82:85], v[66:69], v[20:23]
	v_mfma_f32_16x16x32_bf16 v[16:19], v[86:89], v[66:69], v[16:19]
	v_mfma_f32_16x16x32_bf16 v[12:15], v[74:77], v[70:73], v[12:15]
	v_mfma_f32_16x16x32_bf16 v[8:11], v[78:81], v[70:73], v[8:11]
	v_mfma_f32_16x16x32_bf16 v[4:7], v[82:85], v[70:73], v[4:7]
	v_mfma_f32_16x16x32_bf16 v[0:3], v[86:89], v[70:73], v[0:3]
	s_cbranch_scc0 .LBB0_458
	ds_write_b128 v52, v[28:31]
	ds_write_b128 v52, v[24:27] offset:64
	ds_write_b128 v52, v[20:23] offset:128
	ds_write_b128 v52, v[16:19] offset:192
	ds_write_b128 v52, v[12:15] offset:4352
	ds_write_b128 v52, v[8:11] offset:4416
	ds_write_b128 v52, v[4:7] offset:4480
	ds_write_b128 v52, v[0:3] offset:4544
	s_waitcnt lgkmcnt(0)
	s_barrier
	ds_read_b128 v[24:27], v53
	ds_read_b128 v[16:19], v53 offset:16
	ds_read_b128 v[28:31], v53 offset:17408
	ds_read_b128 v[12:15], v53 offset:17424
	ds_read_b128 v[32:35], v53 offset:34816
	ds_read_b128 v[8:11], v53 offset:34832
	ds_read_b128 v[36:39], v53 offset:52224
	ds_read_b128 v[4:7], v53 offset:52240
	s_lshl_b32 s24, s24, 4
	s_sub_i32 s24, s12, s24
	v_lshl_or_b32 v44, s24, 6, v50
	v_ashrrev_i32_e32 v45, 31, v44
	v_mov_b32_e32 v0, 0
	s_and_b64 vcc, exec, s[16:17]
	v_lshl_add_u64 v[46:47], v[44:45], 2, s[8:9]
	v_mov_b32_e32 v20, 0
	v_mov_b32_e32 v21, 0
	v_mov_b32_e32 v22, 0
	v_mov_b32_e32 v23, 0
	s_cbranch_vccz .LBB0_461
	global_load_dwordx4 v[20:23], v[46:47], off
